# cross-half row max via v_permlane32_swap instead of ds_bpermute in diff-attn softmax
# baseline (speedup 1.0000x reference)
; template <int NS, int SI>
; __device__ __forceinline__ void attn_stream(const unsigned char* kbase, const unsigned char* vbase, const unsigned char* q_rd, bool mask_tail, int last_valid, int hh, float sc,
;                                             f32x16 (&O)[4], float& mrun, float& lrun) {
;     ...
;     float mx = __builtin_amdgcn_fmed3f(S0[0], S1[0], __builtin_inff());
; #pragma unroll
;     for (int r = 1; r < 16; ++r) { mx = __builtin_amdgcn_fmed3f(mx, S0[r], __builtin_inff()); mx = __builtin_amdgcn_fmed3f(mx, S1[r], __builtin_inff()); }
;     mx = fmaxf(mx, __shfl_xor(mx, 32));
;     const float mn = fmaxf(mrun, mx * sc);
;     const float alpha = __builtin_amdgcn_exp2f(mrun - mn);
.LBB0_1165:
	s_nop 9
	v_max_f32_e32 v200, v144, v144
	v_max_f32_e32 v202, v128, v128
	v_max_f32_e32 v200, v202, v200
	v_max3_f32 v200, v200, v129, v145
	v_max3_f32 v200, v200, v130, v146
	v_max3_f32 v200, v200, v131, v147
	v_max3_f32 v200, v200, v132, v148
	v_max3_f32 v200, v200, v133, v149
	v_max3_f32 v200, v200, v134, v150
	v_max3_f32 v200, v200, v135, v151
	v_max3_f32 v200, v200, v136, v152
	v_max3_f32 v200, v200, v137, v153
	v_max3_f32 v200, v200, v138, v154
	v_max3_f32 v200, v200, v139, v155
	v_max3_f32 v200, v200, v140, v156
	v_max3_f32 v200, v200, v141, v157
	v_max3_f32 v200, v200, v142, v158
	v_max3_f32 v200, v200, v143, v159
	v_mov_b32_e32 v202, v200
	s_nop 1
	v_permlane32_swap_b32_e32 v202, v200
	v_max_f32_e32 v200, v200, v202
	v_mul_f32_e32 v200, 0x3e38aa3b, v200
	v_max_f32_e32 v202, v228, v228
	v_max_f32_e32 v200, v202, v200
	v_sub_f32_e32 v202, v200, v228
	v_cmp_lt_f32_e32 vcc, 4.0, v202
	s_nop 1
	v_cndmask_b32_e32 v200, v228, v200, vcc
	v_sub_f32_e32 v202, v228, v200
	v_exp_f32_e32 v202, v202
	s_nop 0
	v_cmp_neq_f32_e32 vcc, 1.0, v202
	s_cbranch_vccz .LBB0_1167
	v_pk_mul_f32 v[78:79], v[78:79], v[202:203] op_sel_hi:[1,0]
	v_pk_mul_f32 v[76:77], v[76:77], v[202:203] op_sel_hi:[1,0]
	v_pk_mul_f32 v[74:75], v[74:75], v[202:203] op_sel_hi:[1,0]
	v_pk_mul_f32 v[72:73], v[72:73], v[202:203] op_sel_hi:[1,0]
	v_pk_mul_f32 v[70:71], v[70:71], v[202:203] op_sel_hi:[1,0]
	v_pk_mul_f32 v[68:69], v[68:69], v[202:203] op_sel_hi:[1,0]
	v_pk_mul_f32 v[66:67], v[66:67], v[202:203] op_sel_hi:[1,0]
	v_pk_mul_f32 v[64:65], v[64:65], v[202:203] op_sel_hi:[1,0]
	v_pk_mul_f32 v[62:63], v[62:63], v[202:203] op_sel_hi:[1,0]
	v_pk_mul_f32 v[60:61], v[60:61], v[202:203] op_sel_hi:[1,0]
	v_pk_mul_f32 v[58:59], v[58:59], v[202:203] op_sel_hi:[1,0]
	v_pk_mul_f32 v[56:57], v[56:57], v[202:203] op_sel_hi:[1,0]
	v_pk_mul_f32 v[54:55], v[54:55], v[202:203] op_sel_hi:[1,0]
	v_pk_mul_f32 v[52:53], v[52:53], v[202:203] op_sel_hi:[1,0]
	v_pk_mul_f32 v[50:51], v[50:51], v[202:203] op_sel_hi:[1,0]
	v_pk_mul_f32 v[48:49], v[48:49], v[202:203] op_sel_hi:[1,0]
	v_pk_mul_f32 v[46:47], v[46:47], v[202:203] op_sel_hi:[1,0]
	v_pk_mul_f32 v[44:45], v[44:45], v[202:203] op_sel_hi:[1,0]
	v_pk_mul_f32 v[42:43], v[42:43], v[202:203] op_sel_hi:[1,0]
	v_pk_mul_f32 v[40:41], v[40:41], v[202:203] op_sel_hi:[1,0]
	v_pk_mul_f32 v[38:39], v[38:39], v[202:203] op_sel_hi:[1,0]
	v_pk_mul_f32 v[36:37], v[36:37], v[202:203] op_sel_hi:[1,0]
	v_pk_mul_f32 v[34:35], v[34:35], v[202:203] op_sel_hi:[1,0]
	v_pk_mul_f32 v[32:33], v[32:33], v[202:203] op_sel_hi:[1,0]
	v_pk_mul_f32 v[14:15], v[14:15], v[202:203] op_sel_hi:[1,0]
	v_pk_mul_f32 v[12:13], v[12:13], v[202:203] op_sel_hi:[1,0]
	v_pk_mul_f32 v[10:11], v[10:11], v[202:203] op_sel_hi:[1,0]
	v_pk_mul_f32 v[8:9], v[8:9], v[202:203] op_sel_hi:[1,0]
	v_pk_mul_f32 v[6:7], v[6:7], v[202:203] op_sel_hi:[1,0]
	v_pk_mul_f32 v[4:5], v[4:5], v[202:203] op_sel_hi:[1,0]
	v_pk_mul_f32 v[2:3], v[2:3], v[202:203] op_sel_hi:[1,0]
	v_pk_mul_f32 v[0:1], v[0:1], v[202:203] op_sel_hi:[1,0]

; template <int NS, int SI>
; __device__ __forceinline__ void attn_stream(const unsigned char* kbase, const unsigned char* vbase, const unsigned char* q_rd, bool mask_tail, int last_valid, int hh, float sc,
;                                             f32x16 (&O)[4], float& mrun, float& lrun) {
;     ...
;     float mx = __builtin_amdgcn_fmed3f(S0[0], S1[0], __builtin_inff());
; #pragma unroll
;     for (int r = 1; r < 16; ++r) { mx = __builtin_amdgcn_fmed3f(mx, S0[r], __builtin_inff()); mx = __builtin_amdgcn_fmed3f(mx, S1[r], __builtin_inff()); }
;     mx = fmaxf(mx, __shfl_xor(mx, 32));
;     const float mn = fmaxf(mrun, mx * sc);
;     const float alpha = __builtin_amdgcn_exp2f(mrun - mn);
.LBB0_1177:
	s_nop 9
	v_max_f32_e32 v200, v144, v144
	v_max_f32_e32 v202, v128, v128
	v_max_f32_e32 v200, v202, v200
	v_max3_f32 v200, v200, v129, v145
	v_max3_f32 v200, v200, v130, v146
	v_max3_f32 v200, v200, v131, v147
	v_max3_f32 v200, v200, v132, v148
	v_max3_f32 v200, v200, v133, v149
	v_max3_f32 v200, v200, v134, v150
	v_max3_f32 v200, v200, v135, v151
	v_max3_f32 v200, v200, v136, v152
	v_max3_f32 v200, v200, v137, v153
	v_max3_f32 v200, v200, v138, v154
	v_max3_f32 v200, v200, v139, v155
	v_max3_f32 v200, v200, v140, v156
	v_max3_f32 v200, v200, v141, v157
	v_max3_f32 v200, v200, v142, v158
	v_max3_f32 v200, v200, v143, v159
	v_mov_b32_e32 v202, v200
	s_nop 1
	v_permlane32_swap_b32_e32 v202, v200
	v_max_f32_e32 v200, v200, v202
	v_mul_f32_e32 v200, 0x3e38aa3b, v200
	v_max_f32_e32 v202, v229, v229
	v_max_f32_e32 v200, v202, v200
	v_sub_f32_e32 v202, v200, v229
	v_cmp_lt_f32_e32 vcc, 4.0, v202
	s_nop 1
	v_cndmask_b32_e32 v200, v229, v200, vcc
	v_sub_f32_e32 v202, v229, v200
	v_exp_f32_e32 v202, v202
	s_nop 0
	v_cmp_neq_f32_e32 vcc, 1.0, v202
	s_cbranch_vccz .LBB0_1179
	v_pk_mul_f32 v[126:127], v[126:127], v[202:203] op_sel_hi:[1,0]
	v_pk_mul_f32 v[124:125], v[124:125], v[202:203] op_sel_hi:[1,0]
	v_pk_mul_f32 v[122:123], v[122:123], v[202:203] op_sel_hi:[1,0]
	v_pk_mul_f32 v[120:121], v[120:121], v[202:203] op_sel_hi:[1,0]
	v_pk_mul_f32 v[118:119], v[118:119], v[202:203] op_sel_hi:[1,0]
	v_pk_mul_f32 v[116:117], v[116:117], v[202:203] op_sel_hi:[1,0]
	v_pk_mul_f32 v[114:115], v[114:115], v[202:203] op_sel_hi:[1,0]
	v_pk_mul_f32 v[112:113], v[112:113], v[202:203] op_sel_hi:[1,0]
	v_pk_mul_f32 v[110:111], v[110:111], v[202:203] op_sel_hi:[1,0]
	v_pk_mul_f32 v[108:109], v[108:109], v[202:203] op_sel_hi:[1,0]
	v_pk_mul_f32 v[106:107], v[106:107], v[202:203] op_sel_hi:[1,0]
	v_pk_mul_f32 v[104:105], v[104:105], v[202:203] op_sel_hi:[1,0]
	v_pk_mul_f32 v[102:103], v[102:103], v[202:203] op_sel_hi:[1,0]
	v_pk_mul_f32 v[100:101], v[100:101], v[202:203] op_sel_hi:[1,0]
	v_pk_mul_f32 v[98:99], v[98:99], v[202:203] op_sel_hi:[1,0]
	v_pk_mul_f32 v[96:97], v[96:97], v[202:203] op_sel_hi:[1,0]
	v_pk_mul_f32 v[94:95], v[94:95], v[202:203] op_sel_hi:[1,0]
	v_pk_mul_f32 v[92:93], v[92:93], v[202:203] op_sel_hi:[1,0]
	v_pk_mul_f32 v[90:91], v[90:91], v[202:203] op_sel_hi:[1,0]
	v_pk_mul_f32 v[88:89], v[88:89], v[202:203] op_sel_hi:[1,0]
	v_pk_mul_f32 v[86:87], v[86:87], v[202:203] op_sel_hi:[1,0]
	v_pk_mul_f32 v[84:85], v[84:85], v[202:203] op_sel_hi:[1,0]
	v_pk_mul_f32 v[82:83], v[82:83], v[202:203] op_sel_hi:[1,0]
	v_pk_mul_f32 v[80:81], v[80:81], v[202:203] op_sel_hi:[1,0]
	v_pk_mul_f32 v[30:31], v[30:31], v[202:203] op_sel_hi:[1,0]
	v_pk_mul_f32 v[28:29], v[28:29], v[202:203] op_sel_hi:[1,0]
	v_pk_mul_f32 v[26:27], v[26:27], v[202:203] op_sel_hi:[1,0]
	v_pk_mul_f32 v[24:25], v[24:25], v[202:203] op_sel_hi:[1,0]
	v_pk_mul_f32 v[22:23], v[22:23], v[202:203] op_sel_hi:[1,0]
	v_pk_mul_f32 v[20:21], v[20:21], v[202:203] op_sel_hi:[1,0]
	v_pk_mul_f32 v[18:19], v[18:19], v[202:203] op_sel_hi:[1,0]
	v_pk_mul_f32 v[16:17], v[16:17], v[202:203] op_sel_hi:[1,0]
